# FoX key loop: forget-bias add/mul deferred to the end-of-step LDS store instead of waiting vmcnt(0) at the top of every step (wave 0)
# baseline (speedup 1.0000x reference)
.LBB0_501:
	s_cmpk_eq_i32 s59, 0xff00
	s_mov_b64 s[22:23], -1
	s_cbranch_scc1 .LBB0_507
	s_cmp_lt_u32 s75, s69
	s_cselect_b64 s[22:23], -1, 0
	s_cmp_ge_u32 s75, s69
	s_cbranch_scc1 .LBB0_508
	v_lshl_add_u64 v[32:33], s[90:91], 0, v[180:181]
	v_lshl_add_u64 v[34:35], s[90:91], 0, v[176:177]
	global_load_dwordx4 v[82:85], v[32:33], off
	global_load_dwordx4 v[86:89], v[34:35], off
	s_and_saveexec_b64 s[26:27], s[50:51]
	s_cbranch_execz .LBB0_505
	v_lshl_add_u64 v[32:33], s[90:91], 0, v[178:179]
	global_load_dword v250, v[32:33], off
	v_add_u32_e32 v33, s59, v203
	v_ashrrev_i32_e32 v33, 7, v33
	v_lshl_add_u32 v33, v33, 2, 0
	ds_read_b32 v251, v33 offset:36352

.LBB0_514:
	s_xor_b32 s26, s72, 1
	s_mul_i32 s22, s26, 0x2400
	v_add_u32_e32 v32, s22, v197
	s_mul_i32 s22, s26, 0x2200
	s_waitcnt vmcnt(1)
	ds_write_b128 v32, v[82:85]
	v_add_u32_e32 v32, s22, v192
	v_add_u32_e32 v32, 0x4800, v32
	s_waitcnt vmcnt(0)
	ds_write2_b64 v32, v[86:87], v[88:89] offset1:1
	s_and_saveexec_b64 s[22:23], s[50:51]
	s_waitcnt vmcnt(0) lgkmcnt(0)
	v_add_f32_e32 v153, v250, v251
	v_mul_f32_e32 v153, 0xbfb8aa3b, v153
	v_lshl_add_u32 v32, s26, 8, v198
	ds_write_b32 v32, v153 offset:35840
	s_or_b64 exec, exec, s[22:23]
